# v91 + hand-written LN1 (double-buffered tokens, contiguous-lane 1 KB loads/stores, DPP wave sums)
# baseline (speedup 1.0000x reference)
.LBB1_70:
	s_and_b64 vcc, exec, s[30:31]
	s_cbranch_vccz .LBB1_75
	s_mov_b64 exec, -1
	s_mov_b64 s[30:31], -1
	v_lshrrev_b32_e32 v146, 6, v162
	v_readlane_b32 s2, v242, 0
	v_readlane_b32 s59, v241, 24
	v_readfirstlane_b32 s12, v146
	s_lshl_b32 s2, s2, 2
	s_add_u32 s54, s2, s12
	s_load_dwordx2 s[94:95], s[0:1], 0xc8
	v_lshlrev_b32_e32 v160, 4, v168
	v_lshlrev_b32_e32 v161, 3, v168
	v_readlane_b32 s40, v240, 12
	v_readlane_b32 s41, v240, 13
	v_readlane_b32 s42, v240, 14
	v_readlane_b32 s43, v240, 15
	s_nop 3
	s_sub_u32 s40, s40, 0x1000
	s_subb_u32 s41, s41, 0
	s_sub_u32 s42, s42, 0x1000
	s_subb_u32 s43, s43, 0
	s_waitcnt lgkmcnt(0)
	global_load_dwordx4 v[80:83], v160, s[40:41] offset:0
	global_load_dwordx4 v[84:87], v160, s[40:41] offset:1024
	global_load_dwordx4 v[88:91], v160, s[40:41] offset:2048
	global_load_dwordx4 v[92:95], v160, s[40:41] offset:3072
	global_load_dwordx4 v[96:99], v160, s[42:43] offset:0
	global_load_dwordx4 v[100:103], v160, s[42:43] offset:1024
	global_load_dwordx4 v[104:107], v160, s[42:43] offset:2048
	global_load_dwordx4 v[108:111], v160, s[42:43] offset:3072
	s_cmp_lt_u32 s54, 0x4200
	s_cbranch_scc0 .Lln1_done
	s_min_u32 s15, s54, 0x41ff
	s_lshl_b32 s50, s15, 12
	s_add_u32 s52, s72, s50
	s_addc_u32 s53, s73, 0
	global_load_dwordx4 v[48:51], v160, s[52:53] offset:0
	global_load_dwordx4 v[52:55], v160, s[52:53] offset:1024
	global_load_dwordx4 v[56:59], v160, s[52:53] offset:2048
	global_load_dwordx4 v[60:63], v160, s[52:53] offset:3072
	s_cmp_lt_u32 s15, 0x2000
	s_cselect_b32 s14, 0, 1
	s_cmp_lt_u32 s15, 0x4000
	s_cselect_b32 s14, s14, 2
	s_add_u32 s16, s14, s27
	s_mul_i32 s16, s16, 0x6000
	s_add_u32 s16, s16, 0x3000
	s_add_u32 s46, s94, s16
	s_addc_u32 s47, s95, 0
	global_load_dwordx4 v[112:115], v160, s[46:47] offset:0
	global_load_dwordx4 v[116:119], v160, s[46:47] offset:1024
	global_load_dwordx4 v[120:123], v160, s[46:47] offset:2048
	global_load_dwordx4 v[124:127], v160, s[46:47] offset:3072
	s_add_u32 s46, s46, 0x1000
	s_addc_u32 s47, s47, 0
	global_load_dwordx4 v[130:133], v160, s[46:47] offset:0
	global_load_dwordx4 v[134:137], v160, s[46:47] offset:1024
	global_load_dwordx4 v[138:141], v160, s[46:47] offset:2048
	global_load_dwordx4 v[142:145], v160, s[46:47] offset:3072
.Lln1_tok:
	s_mov_b32 s2, s54
	s_add_u32 s99, s54, s59
	s_min_u32 s15, s99, 0x41ff
	s_lshl_b32 s50, s15, 12
	s_add_u32 s52, s72, s50
	s_addc_u32 s53, s73, 0
	global_load_dwordx4 v[0:3], v160, s[52:53] offset:0
	global_load_dwordx4 v[4:7], v160, s[52:53] offset:1024
	global_load_dwordx4 v[8:11], v160, s[52:53] offset:2048
	global_load_dwordx4 v[12:15], v160, s[52:53] offset:3072
	s_cmp_lt_u32 s15, 0x2000
	s_cselect_b32 s14, 0, 1
	s_cmp_lt_u32 s15, 0x4000
	s_cselect_b32 s14, s14, 2
	s_add_u32 s16, s14, s27
	s_mul_i32 s16, s16, 0x6000
	s_add_u32 s16, s16, 0x3000
	s_add_u32 s46, s94, s16
	s_addc_u32 s47, s95, 0
	global_load_dwordx4 v[16:19], v160, s[46:47] offset:0
	global_load_dwordx4 v[20:23], v160, s[46:47] offset:1024
	global_load_dwordx4 v[24:27], v160, s[46:47] offset:2048
	global_load_dwordx4 v[28:31], v160, s[46:47] offset:3072
	s_add_u32 s46, s46, 0x1000
	s_addc_u32 s47, s47, 0
	global_load_dwordx4 v[32:35], v160, s[46:47] offset:0
	global_load_dwordx4 v[36:39], v160, s[46:47] offset:1024
	global_load_dwordx4 v[40:43], v160, s[46:47] offset:2048
	global_load_dwordx4 v[44:47], v160, s[46:47] offset:3072
	s_waitcnt vmcnt(12)
	v_add_f32_e32 v146, v48, v49
	v_add_f32_e32 v146, v146, v50
	v_add_f32_e32 v146, v146, v51
	v_add_f32_e32 v146, v146, v52
	v_add_f32_e32 v146, v146, v53
	v_add_f32_e32 v146, v146, v54
	v_add_f32_e32 v146, v146, v55
	v_add_f32_e32 v146, v146, v56
	v_add_f32_e32 v146, v146, v57
	v_add_f32_e32 v146, v146, v58
	v_add_f32_e32 v146, v146, v59
	v_add_f32_e32 v146, v146, v60
	v_add_f32_e32 v146, v146, v61
	v_add_f32_e32 v146, v146, v62
	v_add_f32_e32 v146, v146, v63
	s_nop 1
	v_add_f32_dpp v146, v146, v146 quad_perm:[1,0,3,2] row_mask:0xf bank_mask:0xf
	s_nop 1
	v_add_f32_dpp v146, v146, v146 quad_perm:[2,3,0,1] row_mask:0xf bank_mask:0xf
	s_nop 1
	v_add_f32_dpp v146, v146, v146 row_half_mirror row_mask:0xf bank_mask:0xf
	s_nop 1
	v_add_f32_dpp v146, v146, v146 row_mirror row_mask:0xf bank_mask:0xf
	s_nop 1
	v_readlane_b32 s8, v146, 0
	v_readlane_b32 s9, v146, 16
	v_readlane_b32 s10, v146, 32
	v_readlane_b32 s11, v146, 48
	s_nop 1
	v_mov_b32_e32 v147, s8
	v_add_f32_e32 v147, s9, v147
	v_add_f32_e32 v147, s10, v147
	v_add_f32_e32 v147, s11, v147
	v_mul_f32_e32 v147, 0x3a800000, v147
	v_sub_f32_e32 v48, v48, v147
	v_sub_f32_e32 v49, v49, v147
	v_sub_f32_e32 v50, v50, v147
	v_sub_f32_e32 v51, v51, v147
	v_sub_f32_e32 v52, v52, v147
	v_sub_f32_e32 v53, v53, v147
	v_sub_f32_e32 v54, v54, v147
	v_sub_f32_e32 v55, v55, v147
	v_sub_f32_e32 v56, v56, v147
	v_sub_f32_e32 v57, v57, v147
	v_sub_f32_e32 v58, v58, v147
	v_sub_f32_e32 v59, v59, v147
	v_sub_f32_e32 v60, v60, v147
	v_sub_f32_e32 v61, v61, v147
	v_sub_f32_e32 v62, v62, v147
	v_sub_f32_e32 v63, v63, v147
	v_mul_f32_e32 v146, v48, v48
	v_mul_f32_e32 v148, v49, v49
	v_add_f32_e32 v146, v146, v148
	v_mul_f32_e32 v148, v50, v50
	v_add_f32_e32 v146, v146, v148
	v_mul_f32_e32 v148, v51, v51
	v_add_f32_e32 v146, v146, v148
	v_mul_f32_e32 v148, v52, v52
	v_add_f32_e32 v146, v146, v148
	v_mul_f32_e32 v148, v53, v53
	v_add_f32_e32 v146, v146, v148
	v_mul_f32_e32 v148, v54, v54
	v_add_f32_e32 v146, v146, v148
	v_mul_f32_e32 v148, v55, v55
	v_add_f32_e32 v146, v146, v148
	v_mul_f32_e32 v148, v56, v56
	v_add_f32_e32 v146, v146, v148
	v_mul_f32_e32 v148, v57, v57
	v_add_f32_e32 v146, v146, v148
	v_mul_f32_e32 v148, v58, v58
	v_add_f32_e32 v146, v146, v148
	v_mul_f32_e32 v148, v59, v59
	v_add_f32_e32 v146, v146, v148
	v_mul_f32_e32 v148, v60, v60
	v_add_f32_e32 v146, v146, v148
	v_mul_f32_e32 v148, v61, v61
	v_add_f32_e32 v146, v146, v148
	v_mul_f32_e32 v148, v62, v62
	v_add_f32_e32 v146, v146, v148
	v_mul_f32_e32 v148, v63, v63
	v_add_f32_e32 v146, v146, v148
	s_nop 1
	v_add_f32_dpp v146, v146, v146 quad_perm:[1,0,3,2] row_mask:0xf bank_mask:0xf
	s_nop 1
	v_add_f32_dpp v146, v146, v146 quad_perm:[2,3,0,1] row_mask:0xf bank_mask:0xf
	s_nop 1
	v_add_f32_dpp v146, v146, v146 row_half_mirror row_mask:0xf bank_mask:0xf
	s_nop 1
	v_add_f32_dpp v146, v146, v146 row_mirror row_mask:0xf bank_mask:0xf
	s_nop 1
	v_readlane_b32 s8, v146, 0
	v_readlane_b32 s9, v146, 16
	v_readlane_b32 s10, v146, 32
	v_readlane_b32 s11, v146, 48
	s_nop 1
	v_mov_b32_e32 v147, s8
	v_add_f32_e32 v147, s9, v147
	v_add_f32_e32 v147, s10, v147
	v_add_f32_e32 v147, s11, v147
	v_fmamk_f32 v147, v147, 0x3a800000, v163
	s_mov_b32 s8, 0x800000
	v_cmp_gt_f32_e32 vcc, s8, v147
	v_mul_f32_e32 v148, 0x4b800000, v147
	s_nop 1
	v_cndmask_b32_e32 v147, v147, v148, vcc
	v_rsq_f32_e32 v147, v147
	s_nop 0
	v_mul_f32_e32 v148, 0x45800000, v147
	v_cndmask_b32_e32 v147, v147, v148, vcc
	v_mul_f32_e32 v48, v48, v147
	v_mul_f32_e32 v49, v49, v147
	v_mul_f32_e32 v50, v50, v147
	v_mul_f32_e32 v51, v51, v147
	v_mul_f32_e32 v52, v52, v147
	v_mul_f32_e32 v53, v53, v147
	v_mul_f32_e32 v54, v54, v147
	v_mul_f32_e32 v55, v55, v147
	v_mul_f32_e32 v56, v56, v147
	v_mul_f32_e32 v57, v57, v147
	v_mul_f32_e32 v58, v58, v147
	v_mul_f32_e32 v59, v59, v147
	v_mul_f32_e32 v60, v60, v147
	v_mul_f32_e32 v61, v61, v147
	v_mul_f32_e32 v62, v62, v147
	v_mul_f32_e32 v63, v63, v147
	v_fma_f32 v48, v80, v48, v96
	v_fma_f32 v49, v81, v49, v97
	v_fma_f32 v50, v82, v50, v98
	v_fma_f32 v51, v83, v51, v99
	v_fma_f32 v52, v84, v52, v100
	v_fma_f32 v53, v85, v53, v101
	v_fma_f32 v54, v86, v54, v102
	v_fma_f32 v55, v87, v55, v103
	v_fma_f32 v56, v88, v56, v104
	v_fma_f32 v57, v89, v57, v105
	v_fma_f32 v58, v90, v58, v106
	v_fma_f32 v59, v91, v59, v107
	v_fma_f32 v60, v92, v60, v108
	v_fma_f32 v61, v93, v61, v109
	v_fma_f32 v62, v94, v62, v110
	v_fma_f32 v63, v95, v63, v111
	s_lshl_b32 s50, s2, 12
	s_add_u32 s52, s70, s50
	s_addc_u32 s53, s71, 0
	global_store_dwordx4 v160, v[48:51], s[52:53] offset:0
	global_store_dwordx4 v160, v[52:55], s[52:53] offset:1024
	global_store_dwordx4 v160, v[56:59], s[52:53] offset:2048
	global_store_dwordx4 v160, v[60:63], s[52:53] offset:3072
	v_add_f32_e32 v130, 1.0, v130
	v_add_f32_e32 v131, 1.0, v131
	v_add_f32_e32 v132, 1.0, v132
	v_add_f32_e32 v133, 1.0, v133
	v_add_f32_e32 v134, 1.0, v134
	v_add_f32_e32 v135, 1.0, v135
	v_add_f32_e32 v136, 1.0, v136
	v_add_f32_e32 v137, 1.0, v137
	v_add_f32_e32 v138, 1.0, v138
	v_add_f32_e32 v139, 1.0, v139
	v_add_f32_e32 v140, 1.0, v140
	v_add_f32_e32 v141, 1.0, v141
	v_add_f32_e32 v142, 1.0, v142
	v_add_f32_e32 v143, 1.0, v143
	v_add_f32_e32 v144, 1.0, v144
	v_add_f32_e32 v145, 1.0, v145
	v_fma_f32 v112, v48, v130, v112
	v_fma_f32 v113, v49, v131, v113
	v_fma_f32 v114, v50, v132, v114
	v_fma_f32 v115, v51, v133, v115
	v_fma_f32 v116, v52, v134, v116
	v_fma_f32 v117, v53, v135, v117
	v_fma_f32 v118, v54, v136, v118
	v_fma_f32 v119, v55, v137, v119
	v_fma_f32 v120, v56, v138, v120
	v_fma_f32 v121, v57, v139, v121
	v_fma_f32 v122, v58, v140, v122
	v_fma_f32 v123, v59, v141, v123
	v_fma_f32 v124, v60, v142, v124
	v_fma_f32 v125, v61, v143, v125
	v_fma_f32 v126, v62, v144, v126
	v_fma_f32 v127, v63, v145, v127
	v_cvt_pk_bf16_f32 v64, v112, v113
	v_cvt_pk_bf16_f32 v65, v114, v115
	v_cvt_pk_bf16_f32 v66, v116, v117
	v_cvt_pk_bf16_f32 v67, v118, v119
	v_cvt_pk_bf16_f32 v68, v120, v121
	v_cvt_pk_bf16_f32 v69, v122, v123
	v_cvt_pk_bf16_f32 v70, v124, v125
	v_cvt_pk_bf16_f32 v71, v126, v127
	s_lshl_b32 s50, s2, 11
	s_add_u32 s46, s74, s50
	s_addc_u32 s47, s75, 0
	global_store_dwordx2 v161, v[64:65], s[46:47] offset:0
	global_store_dwordx2 v161, v[66:67], s[46:47] offset:512
	global_store_dwordx2 v161, v[68:69], s[46:47] offset:1024
	global_store_dwordx2 v161, v[70:71], s[46:47] offset:1536
	s_nop 1
	s_mov_b32 s54, s99
	s_cmp_lt_u32 s54, 0x4200
	s_cbranch_scc0 .Lln1_end
	s_mov_b32 s2, s54
	s_add_u32 s99, s54, s59
	s_min_u32 s15, s99, 0x41ff
	s_lshl_b32 s50, s15, 12
	s_add_u32 s52, s72, s50
	s_addc_u32 s53, s73, 0
	global_load_dwordx4 v[48:51], v160, s[52:53] offset:0
	global_load_dwordx4 v[52:55], v160, s[52:53] offset:1024
	global_load_dwordx4 v[56:59], v160, s[52:53] offset:2048
	global_load_dwordx4 v[60:63], v160, s[52:53] offset:3072
	s_cmp_lt_u32 s15, 0x2000
	s_cselect_b32 s14, 0, 1
	s_cmp_lt_u32 s15, 0x4000
	s_cselect_b32 s14, s14, 2
	s_add_u32 s16, s14, s27
	s_mul_i32 s16, s16, 0x6000
	s_add_u32 s16, s16, 0x3000
	s_add_u32 s46, s94, s16
	s_addc_u32 s47, s95, 0
	global_load_dwordx4 v[112:115], v160, s[46:47] offset:0
	global_load_dwordx4 v[116:119], v160, s[46:47] offset:1024
	global_load_dwordx4 v[120:123], v160, s[46:47] offset:2048
	global_load_dwordx4 v[124:127], v160, s[46:47] offset:3072
	s_add_u32 s46, s46, 0x1000
	s_addc_u32 s47, s47, 0
	global_load_dwordx4 v[130:133], v160, s[46:47] offset:0
	global_load_dwordx4 v[134:137], v160, s[46:47] offset:1024
	global_load_dwordx4 v[138:141], v160, s[46:47] offset:2048
	global_load_dwordx4 v[142:145], v160, s[46:47] offset:3072
	s_waitcnt vmcnt(12)
	v_add_f32_e32 v146, v0, v1
	v_add_f32_e32 v146, v146, v2
	v_add_f32_e32 v146, v146, v3
	v_add_f32_e32 v146, v146, v4
	v_add_f32_e32 v146, v146, v5
	v_add_f32_e32 v146, v146, v6
	v_add_f32_e32 v146, v146, v7
	v_add_f32_e32 v146, v146, v8
	v_add_f32_e32 v146, v146, v9
	v_add_f32_e32 v146, v146, v10
	v_add_f32_e32 v146, v146, v11
	v_add_f32_e32 v146, v146, v12
	v_add_f32_e32 v146, v146, v13
	v_add_f32_e32 v146, v146, v14
	v_add_f32_e32 v146, v146, v15
	s_nop 1
	v_add_f32_dpp v146, v146, v146 quad_perm:[1,0,3,2] row_mask:0xf bank_mask:0xf
	s_nop 1
	v_add_f32_dpp v146, v146, v146 quad_perm:[2,3,0,1] row_mask:0xf bank_mask:0xf
	s_nop 1
	v_add_f32_dpp v146, v146, v146 row_half_mirror row_mask:0xf bank_mask:0xf
	s_nop 1
	v_add_f32_dpp v146, v146, v146 row_mirror row_mask:0xf bank_mask:0xf
	s_nop 1
	v_readlane_b32 s8, v146, 0
	v_readlane_b32 s9, v146, 16
	v_readlane_b32 s10, v146, 32
	v_readlane_b32 s11, v146, 48
	s_nop 1
	v_mov_b32_e32 v147, s8
	v_add_f32_e32 v147, s9, v147
	v_add_f32_e32 v147, s10, v147
	v_add_f32_e32 v147, s11, v147
	v_mul_f32_e32 v147, 0x3a800000, v147
	v_sub_f32_e32 v0, v0, v147
	v_sub_f32_e32 v1, v1, v147
	v_sub_f32_e32 v2, v2, v147
	v_sub_f32_e32 v3, v3, v147
	v_sub_f32_e32 v4, v4, v147
	v_sub_f32_e32 v5, v5, v147
	v_sub_f32_e32 v6, v6, v147
	v_sub_f32_e32 v7, v7, v147
	v_sub_f32_e32 v8, v8, v147
	v_sub_f32_e32 v9, v9, v147
	v_sub_f32_e32 v10, v10, v147
	v_sub_f32_e32 v11, v11, v147
	v_sub_f32_e32 v12, v12, v147
	v_sub_f32_e32 v13, v13, v147
	v_sub_f32_e32 v14, v14, v147
	v_sub_f32_e32 v15, v15, v147
	v_mul_f32_e32 v146, v0, v0
	v_mul_f32_e32 v148, v1, v1
	v_add_f32_e32 v146, v146, v148
	v_mul_f32_e32 v148, v2, v2
	v_add_f32_e32 v146, v146, v148
	v_mul_f32_e32 v148, v3, v3
	v_add_f32_e32 v146, v146, v148
	v_mul_f32_e32 v148, v4, v4
	v_add_f32_e32 v146, v146, v148
	v_mul_f32_e32 v148, v5, v5
	v_add_f32_e32 v146, v146, v148
	v_mul_f32_e32 v148, v6, v6
	v_add_f32_e32 v146, v146, v148
	v_mul_f32_e32 v148, v7, v7
	v_add_f32_e32 v146, v146, v148
	v_mul_f32_e32 v148, v8, v8
	v_add_f32_e32 v146, v146, v148
	v_mul_f32_e32 v148, v9, v9
	v_add_f32_e32 v146, v146, v148
	v_mul_f32_e32 v148, v10, v10
	v_add_f32_e32 v146, v146, v148
	v_mul_f32_e32 v148, v11, v11
	v_add_f32_e32 v146, v146, v148
	v_mul_f32_e32 v148, v12, v12
	v_add_f32_e32 v146, v146, v148
	v_mul_f32_e32 v148, v13, v13
	v_add_f32_e32 v146, v146, v148
	v_mul_f32_e32 v148, v14, v14
	v_add_f32_e32 v146, v146, v148
	v_mul_f32_e32 v148, v15, v15
	v_add_f32_e32 v146, v146, v148
	s_nop 1
	v_add_f32_dpp v146, v146, v146 quad_perm:[1,0,3,2] row_mask:0xf bank_mask:0xf
	s_nop 1
	v_add_f32_dpp v146, v146, v146 quad_perm:[2,3,0,1] row_mask:0xf bank_mask:0xf
	s_nop 1
	v_add_f32_dpp v146, v146, v146 row_half_mirror row_mask:0xf bank_mask:0xf
	s_nop 1
	v_add_f32_dpp v146, v146, v146 row_mirror row_mask:0xf bank_mask:0xf
	s_nop 1
	v_readlane_b32 s8, v146, 0
	v_readlane_b32 s9, v146, 16
	v_readlane_b32 s10, v146, 32
	v_readlane_b32 s11, v146, 48
	s_nop 1
	v_mov_b32_e32 v147, s8
	v_add_f32_e32 v147, s9, v147
	v_add_f32_e32 v147, s10, v147
	v_add_f32_e32 v147, s11, v147
	v_fmamk_f32 v147, v147, 0x3a800000, v163
	s_mov_b32 s8, 0x800000
	v_cmp_gt_f32_e32 vcc, s8, v147
	v_mul_f32_e32 v148, 0x4b800000, v147
	s_nop 1
	v_cndmask_b32_e32 v147, v147, v148, vcc
	v_rsq_f32_e32 v147, v147
	s_nop 0
	v_mul_f32_e32 v148, 0x45800000, v147
	v_cndmask_b32_e32 v147, v147, v148, vcc
	v_mul_f32_e32 v0, v0, v147
	v_mul_f32_e32 v1, v1, v147
	v_mul_f32_e32 v2, v2, v147
	v_mul_f32_e32 v3, v3, v147
	v_mul_f32_e32 v4, v4, v147
	v_mul_f32_e32 v5, v5, v147
	v_mul_f32_e32 v6, v6, v147
	v_mul_f32_e32 v7, v7, v147
	v_mul_f32_e32 v8, v8, v147
	v_mul_f32_e32 v9, v9, v147
	v_mul_f32_e32 v10, v10, v147
	v_mul_f32_e32 v11, v11, v147
	v_mul_f32_e32 v12, v12, v147
	v_mul_f32_e32 v13, v13, v147
	v_mul_f32_e32 v14, v14, v147
	v_mul_f32_e32 v15, v15, v147
	v_fma_f32 v0, v80, v0, v96
	v_fma_f32 v1, v81, v1, v97
	v_fma_f32 v2, v82, v2, v98
	v_fma_f32 v3, v83, v3, v99
	v_fma_f32 v4, v84, v4, v100
	v_fma_f32 v5, v85, v5, v101
	v_fma_f32 v6, v86, v6, v102
	v_fma_f32 v7, v87, v7, v103
	v_fma_f32 v8, v88, v8, v104
	v_fma_f32 v9, v89, v9, v105
	v_fma_f32 v10, v90, v10, v106
	v_fma_f32 v11, v91, v11, v107
	v_fma_f32 v12, v92, v12, v108
	v_fma_f32 v13, v93, v13, v109
	v_fma_f32 v14, v94, v14, v110
	v_fma_f32 v15, v95, v15, v111
	s_lshl_b32 s50, s2, 12
	s_add_u32 s52, s70, s50
	s_addc_u32 s53, s71, 0
	global_store_dwordx4 v160, v[0:3], s[52:53] offset:0
	global_store_dwordx4 v160, v[4:7], s[52:53] offset:1024
	global_store_dwordx4 v160, v[8:11], s[52:53] offset:2048
	global_store_dwordx4 v160, v[12:15], s[52:53] offset:3072
	v_add_f32_e32 v32, 1.0, v32
	v_add_f32_e32 v33, 1.0, v33
	v_add_f32_e32 v34, 1.0, v34
	v_add_f32_e32 v35, 1.0, v35
	v_add_f32_e32 v36, 1.0, v36
	v_add_f32_e32 v37, 1.0, v37
	v_add_f32_e32 v38, 1.0, v38
	v_add_f32_e32 v39, 1.0, v39
	v_add_f32_e32 v40, 1.0, v40
	v_add_f32_e32 v41, 1.0, v41
	v_add_f32_e32 v42, 1.0, v42
	v_add_f32_e32 v43, 1.0, v43
	v_add_f32_e32 v44, 1.0, v44
	v_add_f32_e32 v45, 1.0, v45
	v_add_f32_e32 v46, 1.0, v46
	v_add_f32_e32 v47, 1.0, v47
	v_fma_f32 v16, v0, v32, v16
	v_fma_f32 v17, v1, v33, v17
	v_fma_f32 v18, v2, v34, v18
	v_fma_f32 v19, v3, v35, v19
	v_fma_f32 v20, v4, v36, v20
	v_fma_f32 v21, v5, v37, v21
	v_fma_f32 v22, v6, v38, v22
	v_fma_f32 v23, v7, v39, v23
	v_fma_f32 v24, v8, v40, v24
	v_fma_f32 v25, v9, v41, v25
	v_fma_f32 v26, v10, v42, v26
	v_fma_f32 v27, v11, v43, v27
	v_fma_f32 v28, v12, v44, v28
	v_fma_f32 v29, v13, v45, v29
	v_fma_f32 v30, v14, v46, v30
	v_fma_f32 v31, v15, v47, v31
	v_cvt_pk_bf16_f32 v64, v16, v17
	v_cvt_pk_bf16_f32 v65, v18, v19
	v_cvt_pk_bf16_f32 v66, v20, v21
	v_cvt_pk_bf16_f32 v67, v22, v23
	v_cvt_pk_bf16_f32 v68, v24, v25
	v_cvt_pk_bf16_f32 v69, v26, v27
	v_cvt_pk_bf16_f32 v70, v28, v29
	v_cvt_pk_bf16_f32 v71, v30, v31
	s_lshl_b32 s50, s2, 11
	s_add_u32 s46, s74, s50
	s_addc_u32 s47, s75, 0
	global_store_dwordx2 v161, v[64:65], s[46:47] offset:0
	global_store_dwordx2 v161, v[66:67], s[46:47] offset:512
	global_store_dwordx2 v161, v[68:69], s[46:47] offset:1024
	global_store_dwordx2 v161, v[70:71], s[46:47] offset:1536
	s_nop 1
	s_mov_b32 s54, s99
	s_cmp_lt_u32 s54, 0x4200
	s_cbranch_scc1 .Lln1_tok
